# attention loop: LDS-DMA issue via SALU + saddr form (no per-tile 64-bit VALU address math), scalar tile-skip tests, cross-half max combine only on rescale path
# speedup vs baseline: 1.0458x; 1.0068x over previous
.LBB0_877:
	s_or_b64 exec, exec, s[0:1]
	v_mov_b32_e32 v1, v254
	s_waitcnt lgkmcnt(0)
	s_barrier
	s_cmp_lg_u32 0, -1
	v_lshrrev_b32_e32 v5, 2, v1
	v_lshrrev_b32_e32 v2, 5, v1
	v_lshlrev_b32_e32 v4, 2, v1
	v_and_b32_e32 v6, 2, v5
	v_and_or_b32 v4, v4, 12, v6
	v_xor_b32_e32 v6, v2, v5
	v_and_or_b32 v4, v6, 1, v4
	v_lshrrev_b32_e32 v6, 1, v1
	v_and_b32_e32 v0, 31, v1
	v_xor_b32_e32 v2, v2, v6
	v_lshlrev_b32_e32 v7, 7, v0
	v_lshlrev_b32_e32 v2, 4, v2
	v_lshlrev_b32_e32 v6, 3, v1
	v_bfe_u32 v3, v1, 5, 1
	v_and_or_b32 v2, v2, 16, v7
	v_and_b32_e32 v7, 0x60, v6
	v_bfe_u32 v8, v1, 2, 2
	v_and_b32_e32 v6, 8, v6
	s_cselect_b32 s0, 0, 0
	v_lshrrev_b32_e32 v9, 3, v1
	v_lshlrev_b32_e32 v12, 10, v3
	v_lshlrev_b32_e32 v13, 8, v8
	v_add_u32_e32 v6, s0, v6
	v_and_b32_e32 v10, 2, v9
	v_bfe_u32 v11, v1, 1, 1
	v_add3_u32 v6, v6, v12, v13
	v_or_b32_e32 v13, 2, v3
	v_lshlrev_b32_e32 v0, 8, v0
	v_bitop3_b32 v12, v10, v3, v11 bitop3:0x36
	v_bitop3_b32 v10, v10, v13, v11 bitop3:0x36
	v_lshl_or_b32 v198, v4, 4, v0
	v_lshlrev_b32_e32 v0, 4, v1
	v_lshlrev_b32_e32 v10, 4, v10
	s_movk_i32 s0, 0x800
	v_lshlrev_b32_e32 v8, 6, v8
	s_movk_i32 s16, 0x4000
	v_and_b32_e32 v0, 0x1f0, v0
	v_lshl_add_u32 v12, v12, 4, v6
	v_add3_u32 v6, v6, v10, s0
	v_xor_b32_e32 v10, 64, v8
	v_or3_b32 v199, v2, v7, s16
	v_lshl_or_b32 v2, v3, 9, v0
	v_mov_b32_e32 v0, 0
	v_add_u32_e32 v188, v12, v8
	v_add_u32_e32 v189, v6, v8
	v_add_u32_e32 v192, v12, v10
	v_add_u32_e32 v193, v6, v10
	v_xor_b32_e32 v10, 0x80, v8
	v_xor_b32_e32 v8, 0xc0, v8
	v_mov_b32_e32 v3, v0
	v_add_u32_e32 v196, v12, v8
	v_add_u32_e32 v197, v6, v8
	v_lshl_add_u64 v[162:163], s[36:37], 0, v[2:3]
	v_and_b32_e32 v2, 15, v1
	v_and_b32_e32 v5, 12, v5
	v_bfe_u32 v8, v1, 6, 2
	v_bitop3_b32 v2, v5, v2, v8 bitop3:0x36
	s_not_b32 s0, s2
	v_add_u32_e32 v3, 0x200, v1
	v_lshrrev_b32_e32 v4, 4, v1
	v_lshlrev_b32_e32 v2, 4, v2
	s_movk_i32 s7, 0x180
	s_add_i32 s17, s30, s0
	v_mad_u64_u32 v[164:165], s[0:1], v4, s7, v[2:3]
	v_bfe_u32 v7, v1, 4, 5
	v_lshrrev_b32_e32 v5, 4, v3
	s_mov_b32 s0, 0x1ffffe0
	v_add_u32_e32 v195, v6, v10
	s_movk_i32 s6, 0xc0
	v_ashrrev_i32_e32 v6, 6, v1
	v_ashrrev_i32_e32 v200, 8, v1
	v_and_or_b32 v5, v5, s0, v7
	v_xor_b32_e32 v1, v4, v1
	v_mad_u64_u32 v[166:167], s[0:1], v5, s7, v[2:3]
	v_mul_lo_u32 v5, v9, s6
	v_lshlrev_b32_e32 v1, 3, v1
	v_and_or_b32 v1, v1, 56, v5
	v_mov_b32_e32 v5, 0x100
	v_lshlrev_b32_e32 v4, 10, v6
	v_lshl_add_u32 v168, v1, 1, v5
	v_lshrrev_b32_e32 v1, 9, v3
	v_mul_u32_u24_e32 v1, 0x3000, v1
	v_mul_u32_u24_e32 v3, 0x180, v7
	v_add_u32_e32 v203, 0, v4
	s_mov_b32 s3, 0
	v_add_u32_e32 v194, v12, v10
	v_and_b32_e32 v201, 3, v6
	v_bfe_u32 v202, v6, 1, 1
	v_mov_b32_e32 v165, v0
	v_mov_b32_e32 v167, v0
	v_mov_b32_e32 v169, v0
	s_movk_i32 s36, 0x3000
	v_add3_u32 v170, v1, v3, v2
	v_mov_b32_e32 v171, v0
	s_movk_i32 s37, 0x1000
	s_movk_i32 s40, 0x2000
	v_add_u32_e32 v204, 0x2000, v203
	v_add_u32_e32 v205, 0x4000, v203
	s_mov_b64 s[0:1], 0x1dc06000
	s_mov_b32 s41, 0x8000
	s_mov_b64 s[6:7], 0x1dc0c000
	s_movk_i32 s44, 0xfe0
	s_movk_i32 s45, 0x2200
	s_mov_b32 s50, 0xc000
	s_mov_b32 s51, 0x10000
	s_mov_b32 s52, 0x14000
	s_mov_b32 s53, 0x18000
	v_mbcnt_hi_u32_b32 v191, -1, v186
	v_readfirstlane_b32 s74, v203
	v_readfirstlane_b32 s76, v254
	s_nop 0
	s_bfe_u32 s76, s76, 0x10007
	s_mov_b32 s54, 0
	s_branch .LBB0_879

.LBB0_879:
	s_mul_i32 s9, s54, s30
	s_cmpk_gt_i32 s9, 0x7ff
	s_mov_b32 s14, 5
	s_cbranch_scc1 .LBB0_894
	s_bitcmp0_b32 s54, 0
	s_cselect_b32 s8, s2, s17
	s_add_i32 s9, s8, s9
	s_cmpk_gt_i32 s9, 0x7ff
	s_mov_b32 s14, 7
	s_cbranch_scc1 .LBB0_894
	s_ashr_i32 s12, s9, 6
	s_and_b32 s15, s9, 7
	s_lshr_b32 s9, s9, 2
	s_sub_i32 s14, 31, s12
	s_and_b32 s9, s9, 14
	v_add_u32_e32 v206, s9, v200
	s_lshl_b32 s9, s15, 12
	s_lshl_b32 s55, s14, 7
	s_add_i32 s55, s55, s9
	s_lshr_b32 s9, s55, 8
	s_and_b32 s9, s9, 0xfffff0
	v_add_u32_e32 v172, s9, v206
	s_lshl_b32 s9, s14, 2
	v_lshlrev_b32_e32 v1, 7, v172
	s_and_b32 s9, s9, 0x7c
	v_or3_b32 v1, v1, s9, v201
	v_mad_i64_i32 v[2:3], s[12:13], v1, s36, v[162:163]
	v_add_co_u32_e32 v4, vcc, s37, v2
	global_load_dwordx4 v[98:101], v[2:3], off
	global_load_dwordx4 v[102:105], v[2:3], off offset:1024
	global_load_dwordx4 v[106:109], v[2:3], off offset:2048
	global_load_dwordx4 v[110:113], v[2:3], off offset:3072
	v_addc_co_u32_e32 v5, vcc, 0, v3, vcc
	v_add_co_u32_e32 v2, vcc, s40, v2
	s_lshl_b32 s56, s14, 1
	s_nop 0
	v_addc_co_u32_e32 v3, vcc, 0, v3, vcc
	global_load_dwordx4 v[114:117], v[4:5], off offset:1024
	global_load_dwordx4 v[118:121], v[4:5], off offset:2048
	global_load_dwordx4 v[122:125], v[2:3], off offset:-4096
	global_load_dwordx4 v[126:129], v[4:5], off offset:3072
	global_load_dwordx4 v[130:133], v[2:3], off
	global_load_dwordx4 v[134:137], v[2:3], off offset:1024
	global_load_dwordx4 v[138:141], v[2:3], off offset:2048
	global_load_dwordx4 v[142:145], v[2:3], off offset:3072
	s_mul_i32 s15, s15, 0x180000
	s_add_u32 s12, s42, s15
	s_addc_u32 s13, s43, 0
	v_readfirstlane_b32 s9, v203
	v_lshl_add_u64 v[2:3], s[12:13], 0, v[164:165]
	s_mov_b32 m0, s9
	v_readfirstlane_b32 s9, v204
	global_load_lds_dwordx4 v[2:3], off
	v_lshl_add_u64 v[2:3], s[12:13], 0, v[166:167]
	s_mov_b32 m0, s9
	v_readfirstlane_b32 s9, v205
	global_load_lds_dwordx4 v[2:3], off
	v_lshl_add_u64 v[2:3], s[12:13], 0, v[168:169]
	s_mov_b32 m0, s9
	s_add_i32 s8, s3, s8
	global_load_lds_dwordx4 v[2:3], off
	s_and_b32 s8, s8, 7
	v_mov_b32_e32 v14, v0
	v_mov_b32_e32 v15, v0
	s_mul_i32 s8, s8, 0x180000
	v_mov_b32_e32 v1, v0
	v_mov_b32_e32 v2, v0
	v_mov_b32_e32 v3, v0
	v_mov_b32_e32 v4, v0
	v_mov_b32_e32 v5, v0
	v_mov_b32_e32 v6, v0
	v_mov_b32_e32 v7, v0
	v_mov_b32_e32 v8, v0
	v_mov_b32_e32 v9, v0
	v_mov_b32_e32 v10, v0
	v_mov_b32_e32 v11, v0
	v_mov_b32_e32 v12, v0
	v_mov_b32_e32 v13, v0
	v_mov_b64_e32 v[64:65], v[14:15]
	v_mov_b64_e32 v[48:49], v[14:15]
	v_mov_b64_e32 v[32:33], v[14:15]
	s_add_u32 s8, s28, s8
	v_mov_b64_e32 v[62:63], v[12:13]
	v_mov_b64_e32 v[60:61], v[10:11]
	v_mov_b64_e32 v[58:59], v[8:9]
	v_mov_b64_e32 v[56:57], v[6:7]
	v_mov_b64_e32 v[54:55], v[4:5]
	v_mov_b64_e32 v[52:53], v[2:3]
	v_mov_b64_e32 v[50:51], v[0:1]
	v_mov_b64_e32 v[46:47], v[12:13]
	v_mov_b64_e32 v[44:45], v[10:11]
	v_mov_b64_e32 v[42:43], v[8:9]
	v_mov_b64_e32 v[40:41], v[6:7]
	v_mov_b64_e32 v[38:39], v[4:5]
	v_mov_b64_e32 v[36:37], v[2:3]
	v_mov_b64_e32 v[34:35], v[0:1]
	v_mov_b64_e32 v[30:31], v[12:13]
	v_mov_b64_e32 v[28:29], v[10:11]
	v_mov_b64_e32 v[26:27], v[8:9]
	v_mov_b64_e32 v[24:25], v[6:7]
	v_mov_b64_e32 v[22:23], v[4:5]
	v_mov_b64_e32 v[20:21], v[2:3]
	v_mov_b64_e32 v[18:19], v[0:1]
	v_mov_b64_e32 v[16:17], v[14:15]
	s_mov_b32 s57, 0
	s_addc_u32 s9, s29, 0
	v_mov_b64_e32 v[210:211], 0
	v_mov_b64_e32 v[212:213], 0
	v_mov_b64_e32 v[214:215], 0
	v_mov_b64_e32 v[216:217], 0
	v_mov_b64_e32 v[218:219], 0
	v_mov_b64_e32 v[220:221], 0
	v_mov_b64_e32 v[222:223], 0
	v_mov_b64_e32 v[224:225], 0
	v_mov_b32_e32 v173, 0
	v_mov_b64_e32 v[14:15], v[12:13]
	v_mov_b64_e32 v[12:13], v[10:11]
	v_mov_b64_e32 v[10:11], v[8:9]
	v_mov_b64_e32 v[8:9], v[6:7]
	v_mov_b64_e32 v[6:7], v[4:5]
	v_mov_b64_e32 v[4:5], v[2:3]
	v_mov_b64_e32 v[2:3], v[0:1]
	s_or_b32 s75, s56, s76
	s_waitcnt vmcnt(0) lgkmcnt(0)
	s_barrier
	s_branch .LBB0_884
.LBB0_883:
	s_add_i32 s57, s57, 2
	s_add_u32 s8, s8, 0xc000
	s_addc_u32 s9, s9, 0
	s_and_b64 vcc, exec, s[12:13]
	s_waitcnt vmcnt(0) lgkmcnt(0)
	s_barrier
	s_cbranch_vccnz .LBB0_893
.LBB0_884:
	s_add_u32 s72, s8, s0
	s_addc_u32 s73, s9, s1
	s_add_u32 m0, s74, 0x6000
	s_nop 0
	global_load_lds_dwordx4 v164, s[72:73]
	s_add_u32 m0, s74, 0x8000
	s_nop 0
	global_load_lds_dwordx4 v170, s[72:73]
	s_add_u32 m0, s74, 0xa000
	s_nop 0
	global_load_lds_dwordx4 v168, s[72:73]
	s_cmp_gt_u32 s57, s75
	s_cbranch_scc1 .LBB0_888
	ds_read_b128 v[146:149], v198
	ds_read_b128 v[150:153], v198 offset:8192
	v_xor_b32_e32 v209, 0x20, v198
	ds_read_b128 v[246:249], v209
	ds_read_b128 v[250:253], v209 offset:8192
	v_xor_b32_e32 v190, 0x40, v198
	ds_read_b128 v[180:183], v190
	ds_read_b128 v[184:187], v190 offset:8192
	s_waitcnt lgkmcnt(4)
	v_mfma_f32_32x32x16_bf16 v[82:97], v[146:149], v[98:101], v[210:225]
	v_mfma_f32_32x32x16_bf16 v[66:81], v[150:153], v[98:101], v[210:225]
	v_xor_b32_e32 v209, 0x60, v198
	ds_read_b128 v[146:149], v209
	ds_read_b128 v[150:153], v209 offset:8192
	s_waitcnt lgkmcnt(4)
	v_mfma_f32_32x32x16_bf16 v[82:97], v[246:249], v[102:105], v[82:97]
	v_mfma_f32_32x32x16_bf16 v[66:81], v[250:253], v[102:105], v[66:81]
	v_xor_b32_e32 v190, 0x80, v198
	ds_read_b128 v[246:249], v190
	ds_read_b128 v[250:253], v190 offset:8192
	s_waitcnt lgkmcnt(4)
	v_mfma_f32_32x32x16_bf16 v[82:97], v[180:183], v[106:109], v[82:97]
	v_mfma_f32_32x32x16_bf16 v[66:81], v[184:187], v[106:109], v[66:81]
	v_xor_b32_e32 v209, 0xa0, v198
	ds_read_b128 v[180:183], v209
	ds_read_b128 v[184:187], v209 offset:8192
	s_waitcnt lgkmcnt(4)
	v_mfma_f32_32x32x16_bf16 v[82:97], v[146:149], v[110:113], v[82:97]
	v_mfma_f32_32x32x16_bf16 v[66:81], v[150:153], v[110:113], v[66:81]
	v_xor_b32_e32 v190, 0xc0, v198
	ds_read_b128 v[146:149], v190
	ds_read_b128 v[150:153], v190 offset:8192
	s_waitcnt lgkmcnt(4)
	v_mfma_f32_32x32x16_bf16 v[82:97], v[246:249], v[122:125], v[82:97]
	v_mfma_f32_32x32x16_bf16 v[66:81], v[250:253], v[122:125], v[66:81]
	v_xor_b32_e32 v209, 0xe0, v198
	ds_read_b128 v[246:249], v209
	ds_read_b128 v[250:253], v209 offset:8192
	s_waitcnt lgkmcnt(4)
	v_mfma_f32_32x32x16_bf16 v[82:97], v[180:183], v[114:117], v[82:97]
	v_mfma_f32_32x32x16_bf16 v[66:81], v[184:187], v[114:117], v[66:81]
	ds_read_b128 v[180:183], v199
	ds_read_b128 v[184:187], v199 offset:4096
	s_waitcnt lgkmcnt(4)
	v_mfma_f32_32x32x16_bf16 v[82:97], v[146:149], v[118:121], v[82:97]
	v_mfma_f32_32x32x16_bf16 v[66:81], v[150:153], v[118:121], v[66:81]
	v_xor_b32_e32 v209, 0x20, v199
	ds_read_b128 v[146:149], v209
	ds_read_b128 v[150:153], v209 offset:4096
	s_waitcnt lgkmcnt(4)
	v_mfma_f32_32x32x16_bf16 v[82:97], v[246:249], v[126:129], v[82:97]
	v_mfma_f32_32x32x16_bf16 v[66:81], v[250:253], v[126:129], v[66:81]
	v_xor_b32_e32 v190, 0x40, v199
	ds_read_b128 v[246:249], v190
	ds_read_b128 v[250:253], v190 offset:4096
	s_waitcnt lgkmcnt(4)
	v_mfma_f32_32x32x16_bf16 v[82:97], v[180:183], v[130:133], v[82:97]
	v_mfma_f32_32x32x16_bf16 v[66:81], v[184:187], v[130:133], v[66:81]
	v_xor_b32_e32 v209, 0x60, v199
	ds_read_b128 v[180:183], v209
	ds_read_b128 v[184:187], v209 offset:4096
	s_waitcnt lgkmcnt(4)
	v_mfma_f32_32x32x16_bf16 v[82:97], v[146:149], v[134:137], v[82:97]
	v_mfma_f32_32x32x16_bf16 v[66:81], v[150:153], v[134:137], v[66:81]
	s_waitcnt lgkmcnt(2)
	v_mfma_f32_32x32x16_bf16 v[82:97], v[246:249], v[138:141], v[82:97]
	v_mfma_f32_32x32x16_bf16 v[66:81], v[250:253], v[138:141], v[66:81]
	s_waitcnt lgkmcnt(0)
	v_mfma_f32_32x32x16_bf16 v[66:81], v[184:187], v[142:145], v[66:81]
	v_mfma_f32_32x32x16_bf16 v[82:97], v[180:183], v[142:145], v[82:97]
	ds_read_b64_tr_b16 v[158:159], v188 offset:0
	ds_read_b64_tr_b16 v[160:161], v189 offset:0
	ds_read_b64_tr_b16 v[154:155], v192 offset:0
	ds_read_b64_tr_b16 v[156:157], v193 offset:0
	ds_read_b64_tr_b16 v[150:151], v194 offset:0
	ds_read_b64_tr_b16 v[152:153], v195 offset:0
	ds_read_b64_tr_b16 v[146:147], v196 offset:0
	ds_read_b64_tr_b16 v[148:149], v197 offset:0
	s_nop 2
	v_max3_f32 v1, v66, v67, v68
	v_max3_f32 v180, v69, v70, v71
	v_max3_f32 v1, v1, v72, v73
	v_max3_f32 v180, v180, v74, v75
	v_max3_f32 v1, v1, v76, v77
	v_max3_f32 v180, v180, v78, v79
	v_max3_f32 v1, v1, v80, v81
	v_max3_f32 v181, v82, v83, v84
	v_max3_f32 v182, v85, v86, v87
	v_max3_f32 v181, v181, v88, v89
	v_max3_f32 v182, v182, v90, v91
	v_max3_f32 v181, v181, v92, v93
	v_max3_f32 v182, v182, v94, v95
	v_max3_f32 v181, v181, v96, v97
	v_max3_f32 v1, v1, v180, v181
	v_max_f32_e32 v1, v1, v182
	s_cmp_eq_u32 s57, 0
	s_cbranch_scc1 .Latt_rare0
	v_cmp_lt_f32_e32 vcc, 0x41000000, v1
	s_cbranch_vccz .Latt_common0
.Latt_rare0:
	v_mov_b32_e32 v180, v1
	s_nop 1
	v_permlane32_swap_b32_e32 v1, v180
	v_max_f32_e32 v1, v1, v180
	s_cmp_eq_u32 s57, 0
	s_cselect_b32 s71, 0xf149f2ca, 0
	v_max_f32_e64 v243, v1, s71
	v_max_f32_e32 v242, 0, v1
	v_exp_f32_e64 v242, -v242
	v_sub_f32_e32 v210, v210, v243
	v_sub_f32_e32 v211, v211, v243
	v_sub_f32_e32 v212, v212, v243
	v_sub_f32_e32 v213, v213, v243
	v_sub_f32_e32 v214, v214, v243
	v_sub_f32_e32 v215, v215, v243
	v_sub_f32_e32 v216, v216, v243
	v_sub_f32_e32 v217, v217, v243
	v_sub_f32_e32 v218, v218, v243
	v_sub_f32_e32 v219, v219, v243
	v_sub_f32_e32 v220, v220, v243
	v_sub_f32_e32 v221, v221, v243
	v_sub_f32_e32 v222, v222, v243
	v_sub_f32_e32 v223, v223, v243
	v_sub_f32_e32 v224, v224, v243
	v_sub_f32_e32 v225, v225, v243
	v_sub_f32_e32 v66, v66, v243
	v_sub_f32_e32 v67, v67, v243
	v_sub_f32_e32 v68, v68, v243
	v_sub_f32_e32 v69, v69, v243
	v_sub_f32_e32 v70, v70, v243
	v_sub_f32_e32 v71, v71, v243
	v_sub_f32_e32 v72, v72, v243
	v_sub_f32_e32 v73, v73, v243
	v_sub_f32_e32 v74, v74, v243
	v_sub_f32_e32 v75, v75, v243
	v_sub_f32_e32 v76, v76, v243
	v_sub_f32_e32 v77, v77, v243
	v_sub_f32_e32 v78, v78, v243
	v_sub_f32_e32 v79, v79, v243
	v_sub_f32_e32 v80, v80, v243
	v_sub_f32_e32 v81, v81, v243
	v_sub_f32_e32 v82, v82, v243
	v_sub_f32_e32 v83, v83, v243
	v_sub_f32_e32 v84, v84, v243
	v_sub_f32_e32 v85, v85, v243
	v_sub_f32_e32 v86, v86, v243
	v_sub_f32_e32 v87, v87, v243
	v_sub_f32_e32 v88, v88, v243
	v_sub_f32_e32 v89, v89, v243
	v_sub_f32_e32 v90, v90, v243
	v_sub_f32_e32 v91, v91, v243
	v_sub_f32_e32 v92, v92, v243
	v_sub_f32_e32 v93, v93, v243
	v_sub_f32_e32 v94, v94, v243
	v_sub_f32_e32 v95, v95, v243
	v_sub_f32_e32 v96, v96, v243
	v_sub_f32_e32 v97, v97, v243
	v_mul_f32_e32 v173, v173, v242
	v_pk_mul_f32 v[64:65], v[64:65], v[242:243] op_sel_hi:[1,0]
	v_pk_mul_f32 v[62:63], v[62:63], v[242:243] op_sel_hi:[1,0]
	v_pk_mul_f32 v[60:61], v[60:61], v[242:243] op_sel_hi:[1,0]
	v_pk_mul_f32 v[58:59], v[58:59], v[242:243] op_sel_hi:[1,0]
	v_pk_mul_f32 v[56:57], v[56:57], v[242:243] op_sel_hi:[1,0]
	v_pk_mul_f32 v[54:55], v[54:55], v[242:243] op_sel_hi:[1,0]
	v_pk_mul_f32 v[52:53], v[52:53], v[242:243] op_sel_hi:[1,0]
	v_pk_mul_f32 v[50:51], v[50:51], v[242:243] op_sel_hi:[1,0]
	v_pk_mul_f32 v[48:49], v[48:49], v[242:243] op_sel_hi:[1,0]
	v_pk_mul_f32 v[46:47], v[46:47], v[242:243] op_sel_hi:[1,0]
	v_pk_mul_f32 v[44:45], v[44:45], v[242:243] op_sel_hi:[1,0]
	v_pk_mul_f32 v[42:43], v[42:43], v[242:243] op_sel_hi:[1,0]
	v_pk_mul_f32 v[40:41], v[40:41], v[242:243] op_sel_hi:[1,0]
	v_pk_mul_f32 v[38:39], v[38:39], v[242:243] op_sel_hi:[1,0]
	v_pk_mul_f32 v[36:37], v[36:37], v[242:243] op_sel_hi:[1,0]
	v_pk_mul_f32 v[34:35], v[34:35], v[242:243] op_sel_hi:[1,0]
	v_pk_mul_f32 v[32:33], v[32:33], v[242:243] op_sel_hi:[1,0]
	v_pk_mul_f32 v[30:31], v[30:31], v[242:243] op_sel_hi:[1,0]
	v_pk_mul_f32 v[28:29], v[28:29], v[242:243] op_sel_hi:[1,0]
	v_pk_mul_f32 v[26:27], v[26:27], v[242:243] op_sel_hi:[1,0]
	v_pk_mul_f32 v[24:25], v[24:25], v[242:243] op_sel_hi:[1,0]
	v_pk_mul_f32 v[22:23], v[22:23], v[242:243] op_sel_hi:[1,0]
	v_pk_mul_f32 v[20:21], v[20:21], v[242:243] op_sel_hi:[1,0]
	v_pk_mul_f32 v[18:19], v[18:19], v[242:243] op_sel_hi:[1,0]
	v_pk_mul_f32 v[16:17], v[16:17], v[242:243] op_sel_hi:[1,0]
	v_pk_mul_f32 v[14:15], v[14:15], v[242:243] op_sel_hi:[1,0]
	v_pk_mul_f32 v[12:13], v[12:13], v[242:243] op_sel_hi:[1,0]
	v_pk_mul_f32 v[10:11], v[10:11], v[242:243] op_sel_hi:[1,0]
	v_pk_mul_f32 v[8:9], v[8:9], v[242:243] op_sel_hi:[1,0]
	v_pk_mul_f32 v[6:7], v[6:7], v[242:243] op_sel_hi:[1,0]
	v_pk_mul_f32 v[4:5], v[4:5], v[242:243] op_sel_hi:[1,0]
	v_pk_mul_f32 v[2:3], v[2:3], v[242:243] op_sel_hi:[1,0]

.LBB0_888:
	s_cmp_ge_u32 s57, s56
	s_cselect_b64 s[12:13], -1, 0
	s_and_b64 vcc, exec, s[12:13]
	s_waitcnt vmcnt(0) lgkmcnt(0)
	s_barrier
	s_cbranch_vccnz .LBB0_890
	s_add_u32 s72, s8, s6
	s_addc_u32 s73, s9, s7
	s_mov_b32 m0, s74
	s_nop 0
	global_load_lds_dwordx4 v164, s[72:73]
	s_add_u32 m0, s74, 0x2000
	s_nop 0
	global_load_lds_dwordx4 v170, s[72:73]
	s_add_u32 m0, s74, 0x4000
	s_nop 0
	global_load_lds_dwordx4 v168, s[72:73]
.LBB0_890:
	s_cmp_ge_u32 s57, s75
	s_cbranch_scc1 .LBB0_883
	ds_read_b128 v[146:149], v198 offset:24576
	ds_read_b128 v[150:153], v198 offset:32768
	v_xor_b32_e32 v209, 0x20, v198
	ds_read_b128 v[246:249], v209 offset:24576
	ds_read_b128 v[250:253], v209 offset:32768
	v_xor_b32_e32 v190, 0x40, v198
	ds_read_b128 v[180:183], v190 offset:24576
	ds_read_b128 v[184:187], v190 offset:32768
	s_waitcnt lgkmcnt(4)
	v_mfma_f32_32x32x16_bf16 v[82:97], v[146:149], v[98:101], v[210:225]
	v_mfma_f32_32x32x16_bf16 v[66:81], v[150:153], v[98:101], v[210:225]
	v_xor_b32_e32 v209, 0x60, v198
	ds_read_b128 v[146:149], v209 offset:24576
	ds_read_b128 v[150:153], v209 offset:32768
	s_waitcnt lgkmcnt(4)
	v_mfma_f32_32x32x16_bf16 v[82:97], v[246:249], v[102:105], v[82:97]
	v_mfma_f32_32x32x16_bf16 v[66:81], v[250:253], v[102:105], v[66:81]
	v_xor_b32_e32 v190, 0x80, v198
	ds_read_b128 v[246:249], v190 offset:24576
	ds_read_b128 v[250:253], v190 offset:32768
	s_waitcnt lgkmcnt(4)
	v_mfma_f32_32x32x16_bf16 v[82:97], v[180:183], v[106:109], v[82:97]
	v_mfma_f32_32x32x16_bf16 v[66:81], v[184:187], v[106:109], v[66:81]
	v_xor_b32_e32 v209, 0xa0, v198
	ds_read_b128 v[180:183], v209 offset:24576
	ds_read_b128 v[184:187], v209 offset:32768
	s_waitcnt lgkmcnt(4)
	v_mfma_f32_32x32x16_bf16 v[82:97], v[146:149], v[110:113], v[82:97]
	v_mfma_f32_32x32x16_bf16 v[66:81], v[150:153], v[110:113], v[66:81]
	v_xor_b32_e32 v190, 0xc0, v198
	ds_read_b128 v[146:149], v190 offset:24576
	ds_read_b128 v[150:153], v190 offset:32768
	s_waitcnt lgkmcnt(4)
	v_mfma_f32_32x32x16_bf16 v[82:97], v[246:249], v[122:125], v[82:97]
	v_mfma_f32_32x32x16_bf16 v[66:81], v[250:253], v[122:125], v[66:81]
	v_xor_b32_e32 v209, 0xe0, v198
	ds_read_b128 v[246:249], v209 offset:24576
	ds_read_b128 v[250:253], v209 offset:32768
	s_waitcnt lgkmcnt(4)
	v_mfma_f32_32x32x16_bf16 v[82:97], v[180:183], v[114:117], v[82:97]
	v_mfma_f32_32x32x16_bf16 v[66:81], v[184:187], v[114:117], v[66:81]
	ds_read_b128 v[180:183], v199 offset:24576
	ds_read_b128 v[184:187], v199 offset:28672
	s_waitcnt lgkmcnt(4)
	v_mfma_f32_32x32x16_bf16 v[82:97], v[146:149], v[118:121], v[82:97]
	v_mfma_f32_32x32x16_bf16 v[66:81], v[150:153], v[118:121], v[66:81]
	v_xor_b32_e32 v209, 0x20, v199
	ds_read_b128 v[146:149], v209 offset:24576
	ds_read_b128 v[150:153], v209 offset:28672
	s_waitcnt lgkmcnt(4)
	v_mfma_f32_32x32x16_bf16 v[82:97], v[246:249], v[126:129], v[82:97]
	v_mfma_f32_32x32x16_bf16 v[66:81], v[250:253], v[126:129], v[66:81]
	v_xor_b32_e32 v190, 0x40, v199
	ds_read_b128 v[246:249], v190 offset:24576
	ds_read_b128 v[250:253], v190 offset:28672
	s_waitcnt lgkmcnt(4)
	v_mfma_f32_32x32x16_bf16 v[82:97], v[180:183], v[130:133], v[82:97]
	v_mfma_f32_32x32x16_bf16 v[66:81], v[184:187], v[130:133], v[66:81]
	v_xor_b32_e32 v209, 0x60, v199
	ds_read_b128 v[180:183], v209 offset:24576
	ds_read_b128 v[184:187], v209 offset:28672
	s_waitcnt lgkmcnt(4)
	v_mfma_f32_32x32x16_bf16 v[82:97], v[146:149], v[134:137], v[82:97]
	v_mfma_f32_32x32x16_bf16 v[66:81], v[150:153], v[134:137], v[66:81]
	s_waitcnt lgkmcnt(2)
	v_mfma_f32_32x32x16_bf16 v[82:97], v[246:249], v[138:141], v[82:97]
	v_mfma_f32_32x32x16_bf16 v[66:81], v[250:253], v[138:141], v[66:81]
	s_waitcnt lgkmcnt(0)
	v_mfma_f32_32x32x16_bf16 v[66:81], v[184:187], v[142:145], v[66:81]
	v_mfma_f32_32x32x16_bf16 v[82:97], v[180:183], v[142:145], v[82:97]
	ds_read_b64_tr_b16 v[158:159], v188 offset:0x6000
	ds_read_b64_tr_b16 v[160:161], v189 offset:0x6000
	ds_read_b64_tr_b16 v[154:155], v192 offset:0x6000
	ds_read_b64_tr_b16 v[156:157], v193 offset:0x6000
	ds_read_b64_tr_b16 v[150:151], v194 offset:0x6000
	ds_read_b64_tr_b16 v[152:153], v195 offset:0x6000
	ds_read_b64_tr_b16 v[146:147], v196 offset:0x6000
	ds_read_b64_tr_b16 v[148:149], v197 offset:0x6000
	s_nop 2
	v_max3_f32 v1, v66, v67, v68
	v_max3_f32 v180, v69, v70, v71
	v_max3_f32 v1, v1, v72, v73
	v_max3_f32 v180, v180, v74, v75
	v_max3_f32 v1, v1, v76, v77
	v_max3_f32 v180, v180, v78, v79
	v_max3_f32 v1, v1, v80, v81
	v_max3_f32 v181, v82, v83, v84
	v_max3_f32 v182, v85, v86, v87
	v_max3_f32 v181, v181, v88, v89
	v_max3_f32 v182, v182, v90, v91
	v_max3_f32 v181, v181, v92, v93
	v_max3_f32 v182, v182, v94, v95
	v_max3_f32 v181, v181, v96, v97
	v_max3_f32 v1, v1, v180, v181
	v_max_f32_e32 v1, v1, v182
	v_cmp_lt_f32_e32 vcc, 0x41000000, v1
	s_cbranch_vccz .Latt_common1
.Latt_rare1:
	v_mov_b32_e32 v180, v1
	s_nop 1
	v_permlane32_swap_b32_e32 v1, v180
	v_max_f32_e32 v1, v1, v180
	v_max_f32_e32 v243, 0, v1
	v_max_f32_e32 v242, 0, v1
	v_exp_f32_e64 v242, -v242
	v_sub_f32_e32 v210, v210, v243
	v_sub_f32_e32 v211, v211, v243
	v_sub_f32_e32 v212, v212, v243
	v_sub_f32_e32 v213, v213, v243
	v_sub_f32_e32 v214, v214, v243
	v_sub_f32_e32 v215, v215, v243
	v_sub_f32_e32 v216, v216, v243
	v_sub_f32_e32 v217, v217, v243
	v_sub_f32_e32 v218, v218, v243
	v_sub_f32_e32 v219, v219, v243
	v_sub_f32_e32 v220, v220, v243
	v_sub_f32_e32 v221, v221, v243
	v_sub_f32_e32 v222, v222, v243
	v_sub_f32_e32 v223, v223, v243
	v_sub_f32_e32 v224, v224, v243
	v_sub_f32_e32 v225, v225, v243
	v_sub_f32_e32 v66, v66, v243
	v_sub_f32_e32 v67, v67, v243
	v_sub_f32_e32 v68, v68, v243
	v_sub_f32_e32 v69, v69, v243
	v_sub_f32_e32 v70, v70, v243
	v_sub_f32_e32 v71, v71, v243
	v_sub_f32_e32 v72, v72, v243
	v_sub_f32_e32 v73, v73, v243
	v_sub_f32_e32 v74, v74, v243
	v_sub_f32_e32 v75, v75, v243
	v_sub_f32_e32 v76, v76, v243
	v_sub_f32_e32 v77, v77, v243
	v_sub_f32_e32 v78, v78, v243
	v_sub_f32_e32 v79, v79, v243
	v_sub_f32_e32 v80, v80, v243
	v_sub_f32_e32 v81, v81, v243
	v_sub_f32_e32 v82, v82, v243
	v_sub_f32_e32 v83, v83, v243
	v_sub_f32_e32 v84, v84, v243
	v_sub_f32_e32 v85, v85, v243
	v_sub_f32_e32 v86, v86, v243
	v_sub_f32_e32 v87, v87, v243
	v_sub_f32_e32 v88, v88, v243
	v_sub_f32_e32 v89, v89, v243
	v_sub_f32_e32 v90, v90, v243
	v_sub_f32_e32 v91, v91, v243
	v_sub_f32_e32 v92, v92, v243
	v_sub_f32_e32 v93, v93, v243
	v_sub_f32_e32 v94, v94, v243
	v_sub_f32_e32 v95, v95, v243
	v_sub_f32_e32 v96, v96, v243
	v_sub_f32_e32 v97, v97, v243
	v_mul_f32_e32 v173, v173, v242
	v_pk_mul_f32 v[64:65], v[64:65], v[242:243] op_sel_hi:[1,0]
	v_pk_mul_f32 v[62:63], v[62:63], v[242:243] op_sel_hi:[1,0]
	v_pk_mul_f32 v[60:61], v[60:61], v[242:243] op_sel_hi:[1,0]
	v_pk_mul_f32 v[58:59], v[58:59], v[242:243] op_sel_hi:[1,0]
	v_pk_mul_f32 v[56:57], v[56:57], v[242:243] op_sel_hi:[1,0]
	v_pk_mul_f32 v[54:55], v[54:55], v[242:243] op_sel_hi:[1,0]
	v_pk_mul_f32 v[52:53], v[52:53], v[242:243] op_sel_hi:[1,0]
	v_pk_mul_f32 v[50:51], v[50:51], v[242:243] op_sel_hi:[1,0]
	v_pk_mul_f32 v[48:49], v[48:49], v[242:243] op_sel_hi:[1,0]
	v_pk_mul_f32 v[46:47], v[46:47], v[242:243] op_sel_hi:[1,0]
	v_pk_mul_f32 v[44:45], v[44:45], v[242:243] op_sel_hi:[1,0]
	v_pk_mul_f32 v[42:43], v[42:43], v[242:243] op_sel_hi:[1,0]
	v_pk_mul_f32 v[40:41], v[40:41], v[242:243] op_sel_hi:[1,0]
	v_pk_mul_f32 v[38:39], v[38:39], v[242:243] op_sel_hi:[1,0]
	v_pk_mul_f32 v[36:37], v[36:37], v[242:243] op_sel_hi:[1,0]
	v_pk_mul_f32 v[34:35], v[34:35], v[242:243] op_sel_hi:[1,0]
	v_pk_mul_f32 v[32:33], v[32:33], v[242:243] op_sel_hi:[1,0]
	v_pk_mul_f32 v[30:31], v[30:31], v[242:243] op_sel_hi:[1,0]
	v_pk_mul_f32 v[28:29], v[28:29], v[242:243] op_sel_hi:[1,0]
	v_pk_mul_f32 v[26:27], v[26:27], v[242:243] op_sel_hi:[1,0]
	v_pk_mul_f32 v[24:25], v[24:25], v[242:243] op_sel_hi:[1,0]
	v_pk_mul_f32 v[22:23], v[22:23], v[242:243] op_sel_hi:[1,0]
	v_pk_mul_f32 v[20:21], v[20:21], v[242:243] op_sel_hi:[1,0]
	v_pk_mul_f32 v[18:19], v[18:19], v[242:243] op_sel_hi:[1,0]
	v_pk_mul_f32 v[16:17], v[16:17], v[242:243] op_sel_hi:[1,0]
	v_pk_mul_f32 v[14:15], v[14:15], v[242:243] op_sel_hi:[1,0]
	v_pk_mul_f32 v[12:13], v[12:13], v[242:243] op_sel_hi:[1,0]
	v_pk_mul_f32 v[10:11], v[10:11], v[242:243] op_sel_hi:[1,0]
	v_pk_mul_f32 v[8:9], v[8:9], v[242:243] op_sel_hi:[1,0]
	v_pk_mul_f32 v[6:7], v[6:7], v[242:243] op_sel_hi:[1,0]
	v_pk_mul_f32 v[4:5], v[4:5], v[242:243] op_sel_hi:[1,0]
	v_pk_mul_f32 v[2:3], v[2:3], v[242:243] op_sel_hi:[1,0]
